# single-counter XCD-local barrier (5 LSYNC sites), early L1 invalidate
# baseline (speedup 1.0000x reference)
; __device__ __forceinline__ unsigned xb_ld(unsigned* p)              { return __hip_atomic_load(p, __ATOMIC_RELAXED, __HIP_MEMORY_SCOPE_AGENT); }
; __device__ __forceinline__ unsigned xb_add(unsigned* p, unsigned v) { return __hip_atomic_fetch_add(p, v, __ATOMIC_RELAXED, __HIP_MEMORY_SCOPE_AGENT); }
; #define XB_SPIN(cond, bar) do { unsigned _sp = 0; while (cond) { __builtin_amdgcn_s_sleep(1); \
;     if ((++_sp & 255u) == 0u) { if (xb_ld(&(bar)[XB_TMO])) break; if (_sp > XB_SPIN_CAP) { atomicAdd(&(bar)[XB_TMO], 1u); break; } } } } while (0)
; __device__ __forceinline__ void xcd_local_barrier(const XcdBarrier& b) {
;     asm volatile("s_waitcnt vmcnt(0)" ::: "memory");
;     __syncthreads();
;     if (threadIdx.x == 0) {
;         unsigned* bar = b.bar; const unsigned nloc = b.st[0];
;         const unsigned old = xb_add(&bar[XL_SUB(b.x)], 1u); const unsigned gen = old / nloc;
;         if (old + 1u == (gen + 1u) * nloc) xb_add(&bar[XL_GEN(b.x)], 1u);
;         else XB_SPIN(xb_ld(&bar[XL_GEN(b.x)]) == gen, bar);
;         __builtin_amdgcn_fence(__ATOMIC_ACQUIRE, "agent");
;         asm volatile("s_waitcnt vmcnt(0)" ::: "memory");
;     }
;     __syncthreads();
; }
.LBB0_431:
	s_andn2_saveexec_b64 s[2:3], s[36:37]
	s_cbranch_execz .LBB0_449
	s_waitcnt vmcnt(0)
	s_waitcnt vmcnt(0) lgkmcnt(0)
	s_barrier
	s_and_saveexec_b64 s[4:5], s[24:25]
	s_cbranch_execz .LBB0_448
	v_readlane_b32 s10, v255, 0
	v_readlane_b32 s11, v255, 1
	s_lshl_b32 s12, s69, 8
	s_add_u32 s10, s10, s12
	s_addc_u32 s11, s11, 0
	s_add_u32 s10, s10, 0x7000
	s_addc_u32 s11, s11, 0
	v_mov_b32_e32 v0, s10
	v_mov_b32_e32 v1, s11
	v_mov_b32_e32 v2, 1
	flat_atomic_add v[0:1], v2
	buffer_inv sc1
	s_mov_b32 s12, 0
.Llsync_spin_1:
	flat_load_dword v3, v[0:1] sc1
	s_waitcnt vmcnt(0) lgkmcnt(0)
	v_cmp_gt_u32_e32 vcc, 32, v3
	s_cbranch_vccz .Llsync_done_1
	s_sleep 1
	s_add_u32 s12, s12, 1
	s_cmp_lt_u32 s12, 0x100000
	s_cbranch_scc1 .Llsync_spin_1
.Llsync_done_1:
	s_waitcnt vmcnt(0) lgkmcnt(0)
.LBB0_448:
	s_or_b64 exec, exec, s[4:5]
	s_barrier

; __device__ __forceinline__ unsigned xb_ld(unsigned* p)              { return __hip_atomic_load(p, __ATOMIC_RELAXED, __HIP_MEMORY_SCOPE_AGENT); }
; __device__ __forceinline__ unsigned xb_add(unsigned* p, unsigned v) { return __hip_atomic_fetch_add(p, v, __ATOMIC_RELAXED, __HIP_MEMORY_SCOPE_AGENT); }
; #define XB_SPIN(cond, bar) do { unsigned _sp = 0; while (cond) { __builtin_amdgcn_s_sleep(1); \
;     if ((++_sp & 255u) == 0u) { if (xb_ld(&(bar)[XB_TMO])) break; if (_sp > XB_SPIN_CAP) { atomicAdd(&(bar)[XB_TMO], 1u); break; } } } } while (0)
; __device__ __forceinline__ void xcd_local_barrier(const XcdBarrier& b) {
;     asm volatile("s_waitcnt vmcnt(0)" ::: "memory");
;     __syncthreads();
;     if (threadIdx.x == 0) {
;         unsigned* bar = b.bar; const unsigned nloc = b.st[0];
;         const unsigned old = xb_add(&bar[XL_SUB(b.x)], 1u); const unsigned gen = old / nloc;
;         if (old + 1u == (gen + 1u) * nloc) xb_add(&bar[XL_GEN(b.x)], 1u);
;         else XB_SPIN(xb_ld(&bar[XL_GEN(b.x)]) == gen, bar);
;         __builtin_amdgcn_fence(__ATOMIC_ACQUIRE, "agent");
;         asm volatile("s_waitcnt vmcnt(0)" ::: "memory");
;     }
;     __syncthreads();
; }
.LBB0_541:
	s_waitcnt vmcnt(0)
	s_waitcnt vmcnt(0) lgkmcnt(0)
	s_barrier
	s_and_saveexec_b64 s[6:7], s[24:25]
	s_cbranch_execz .LBB0_557
	v_readlane_b32 s10, v255, 0
	v_readlane_b32 s11, v255, 1
	s_lshl_b32 s12, s69, 8
	s_add_u32 s10, s10, s12
	s_addc_u32 s11, s11, 0
	s_add_u32 s10, s10, 0x7000
	s_addc_u32 s11, s11, 0
	v_mov_b32_e32 v0, s10
	v_mov_b32_e32 v1, s11
	v_mov_b32_e32 v2, 1
	flat_atomic_add v[0:1], v2
	buffer_inv sc1
	s_mov_b32 s12, 0
.Llsync_spin_2:
	flat_load_dword v3, v[0:1] sc1
	s_waitcnt vmcnt(0) lgkmcnt(0)
	v_cmp_gt_u32_e32 vcc, 64, v3
	s_cbranch_vccz .Llsync_done_2
	s_sleep 1
	s_add_u32 s12, s12, 1
	s_cmp_lt_u32 s12, 0x100000
	s_cbranch_scc1 .Llsync_spin_2
.Llsync_done_2:
	s_waitcnt vmcnt(0) lgkmcnt(0)
.LBB0_557:
	s_or_b64 exec, exec, s[6:7]
	s_barrier

; __device__ __forceinline__ unsigned xb_ld(unsigned* p)              { return __hip_atomic_load(p, __ATOMIC_RELAXED, __HIP_MEMORY_SCOPE_AGENT); }
; __device__ __forceinline__ unsigned xb_add(unsigned* p, unsigned v) { return __hip_atomic_fetch_add(p, v, __ATOMIC_RELAXED, __HIP_MEMORY_SCOPE_AGENT); }
; #define XB_SPIN(cond, bar) do { unsigned _sp = 0; while (cond) { __builtin_amdgcn_s_sleep(1); \
;     if ((++_sp & 255u) == 0u) { if (xb_ld(&(bar)[XB_TMO])) break; if (_sp > XB_SPIN_CAP) { atomicAdd(&(bar)[XB_TMO], 1u); break; } } } } while (0)
; __device__ __forceinline__ void xcd_local_barrier(const XcdBarrier& b) {
;     asm volatile("s_waitcnt vmcnt(0)" ::: "memory");
;     __syncthreads();
;     if (threadIdx.x == 0) {
;         unsigned* bar = b.bar; const unsigned nloc = b.st[0];
;         const unsigned old = xb_add(&bar[XL_SUB(b.x)], 1u); const unsigned gen = old / nloc;
;         if (old + 1u == (gen + 1u) * nloc) xb_add(&bar[XL_GEN(b.x)], 1u);
;         else XB_SPIN(xb_ld(&bar[XL_GEN(b.x)]) == gen, bar);
;         __builtin_amdgcn_fence(__ATOMIC_ACQUIRE, "agent");
;         asm volatile("s_waitcnt vmcnt(0)" ::: "memory");
;     }
;     __syncthreads();
; }
.Llsync_spin_3:
	flat_load_dword v3, v[0:1] sc1
	s_waitcnt vmcnt(0) lgkmcnt(0)
	v_cmp_gt_u32_e32 vcc, 96, v3
	s_cbranch_vccz .Llsync_done_3
	s_sleep 1
	s_add_u32 s12, s12, 1
	s_cmp_lt_u32 s12, 0x100000
	s_cbranch_scc1 .Llsync_spin_3
.Llsync_done_3:
	s_waitcnt vmcnt(0) lgkmcnt(0)
.LBB0_705:
	s_or_b64 exec, exec, s[6:7]
	s_barrier

; __device__ __forceinline__ unsigned xb_ld(unsigned* p)              { return __hip_atomic_load(p, __ATOMIC_RELAXED, __HIP_MEMORY_SCOPE_AGENT); }
; __device__ __forceinline__ unsigned xb_add(unsigned* p, unsigned v) { return __hip_atomic_fetch_add(p, v, __ATOMIC_RELAXED, __HIP_MEMORY_SCOPE_AGENT); }
; #define XB_SPIN(cond, bar) do { unsigned _sp = 0; while (cond) { __builtin_amdgcn_s_sleep(1); \
;     if ((++_sp & 255u) == 0u) { if (xb_ld(&(bar)[XB_TMO])) break; if (_sp > XB_SPIN_CAP) { atomicAdd(&(bar)[XB_TMO], 1u); break; } } } } while (0)
; __device__ __forceinline__ void xcd_local_barrier(const XcdBarrier& b) {
;     asm volatile("s_waitcnt vmcnt(0)" ::: "memory");
;     __syncthreads();
;     if (threadIdx.x == 0) {
;         unsigned* bar = b.bar; const unsigned nloc = b.st[0];
;         const unsigned old = xb_add(&bar[XL_SUB(b.x)], 1u); const unsigned gen = old / nloc;
;         if (old + 1u == (gen + 1u) * nloc) xb_add(&bar[XL_GEN(b.x)], 1u);
;         else XB_SPIN(xb_ld(&bar[XL_GEN(b.x)]) == gen, bar);
;         __builtin_amdgcn_fence(__ATOMIC_ACQUIRE, "agent");
;         asm volatile("s_waitcnt vmcnt(0)" ::: "memory");
;     }
;     __syncthreads();
; }
.Llsync_spin_4:
	flat_load_dword v3, v[0:1] sc1
	s_waitcnt vmcnt(0) lgkmcnt(0)
	v_cmp_gt_u32_e32 vcc, 128, v3
	s_cbranch_vccz .Llsync_done_4
	s_sleep 1
	s_add_u32 s12, s12, 1
	s_cmp_lt_u32 s12, 0x100000
	s_cbranch_scc1 .Llsync_spin_4
.Llsync_done_4:
	s_waitcnt vmcnt(0) lgkmcnt(0)
.LBB0_813:
	s_or_b64 exec, exec, s[6:7]
	s_barrier

; __device__ __forceinline__ unsigned xb_ld(unsigned* p)              { return __hip_atomic_load(p, __ATOMIC_RELAXED, __HIP_MEMORY_SCOPE_AGENT); }
; __device__ __forceinline__ unsigned xb_add(unsigned* p, unsigned v) { return __hip_atomic_fetch_add(p, v, __ATOMIC_RELAXED, __HIP_MEMORY_SCOPE_AGENT); }
; #define XB_SPIN(cond, bar) do { unsigned _sp = 0; while (cond) { __builtin_amdgcn_s_sleep(1); \
;     if ((++_sp & 255u) == 0u) { if (xb_ld(&(bar)[XB_TMO])) break; if (_sp > XB_SPIN_CAP) { atomicAdd(&(bar)[XB_TMO], 1u); break; } } } } while (0)
; __device__ __forceinline__ void xcd_local_barrier(const XcdBarrier& b) {
;     asm volatile("s_waitcnt vmcnt(0)" ::: "memory");
;     __syncthreads();
;     if (threadIdx.x == 0) {
;         unsigned* bar = b.bar; const unsigned nloc = b.st[0];
;         const unsigned old = xb_add(&bar[XL_SUB(b.x)], 1u); const unsigned gen = old / nloc;
;         if (old + 1u == (gen + 1u) * nloc) xb_add(&bar[XL_GEN(b.x)], 1u);
;         else XB_SPIN(xb_ld(&bar[XL_GEN(b.x)]) == gen, bar);
;         __builtin_amdgcn_fence(__ATOMIC_ACQUIRE, "agent");
;         asm volatile("s_waitcnt vmcnt(0)" ::: "memory");
;     }
;     __syncthreads();
; }
.Llsync_spin_5:
	flat_load_dword v3, v[0:1] sc1
	s_waitcnt vmcnt(0) lgkmcnt(0)
	v_cmp_gt_u32_e32 vcc, 160, v3
	s_cbranch_vccz .Llsync_done_5
	s_sleep 1
	s_add_u32 s12, s12, 1
	s_cmp_lt_u32 s12, 0x100000
	s_cbranch_scc1 .Llsync_spin_5
.Llsync_done_5:
	s_waitcnt vmcnt(0) lgkmcnt(0)
.LBB0_895:
	s_or_b64 exec, exec, s[6:7]
	s_barrier
